# speedup vs baseline: 1.0067x; 1.0067x over previous
; __device__ __forceinline__ void grid_barrier(unsigned char* bar, unsigned& gen, int* s_flag) {
;   asm volatile("s_waitcnt vmcnt(0)" ::: "memory");
;   __syncthreads();
;   gen += 1;
;   const int tid = threadIdx.x;
;   if (tid == 0) {
;     __builtin_amdgcn_fence(__ATOMIC_RELEASE, "agent");
;     asm volatile("s_waitcnt vmcnt(0)" ::: "memory");
;     unsigned old = __hip_atomic_fetch_add((unsigned*)bar, 1u, __ATOMIC_RELAXED, __HIP_MEMORY_SCOPE_AGENT);
;     *s_flag = (old + 1u == gen * gridDim.x) ? 1 : 0;
;   }
;   __syncthreads();
.LBB0_72:
	s_or_b64 exec, exec, s[0:1]
	v_readlane_b32 s12, v254, 20
	v_readlane_b32 s13, v254, 21
	s_mov_b64 s[0:1], -1
	s_and_b64 vcc, exec, s[12:13]
	s_waitcnt vmcnt(0)
	s_add_i32 s16, s6, 1
	s_barrier
	s_mov_b64 s[0:1], exec
	v_readlane_b32 s12, v253, 48
	v_readlane_b32 s13, v253, 49
	s_and_b64 s[12:13], s[0:1], s[12:13]
	s_mov_b64 exec, s[12:13]
	s_cbranch_execz .LBB0_77
	s_mov_b64 s[12:13], exec
	buffer_wbl2 sc1
	s_waitcnt vmcnt(0)
	s_waitcnt vmcnt(0)
	v_mbcnt_lo_u32_b32 v0, s12, 0
	v_mbcnt_hi_u32_b32 v0, s13, v0
	v_cmp_eq_u32_e32 vcc, 0, v0
	s_and_saveexec_b64 s[14:15], vcc
	s_cbranch_execz .LBB0_76
	s_bcnt1_i32_b64 s2, s[12:13]
	v_readlane_b32 s20, v253, 38
	v_mov_b32_e32 v1, s2
	v_readlane_b32 s22, v253, 40
	v_readlane_b32 s23, v253, 41
	v_readlane_b32 s21, v253, 39
	s_nop 3
	global_atomic_add v1, v153, v1, s[22:23] offset:1024 sc0

; template <int G>
; __global__ void __launch_bounds__(256, 2) fwd_kernel(Params P) {
;     ...
;     if (pass == 0) {
;       grid.sync();
;       if (tid == 0) {
;         int* xcnt = (int*)(P.ws + L::o_bar + 512);
;         int ok = (__hip_atomic_load(xcnt + 8, __ATOMIC_RELAXED, __HIP_MEMORY_SCOPE_AGENT) == 0) ? 1 : 0;
;         for (int q = 0; q < 8; ++q) if (__hip_atomic_load(xcnt + q, __ATOMIC_RELAXED, __HIP_MEMORY_SCOPE_AGENT) <= 0) ok = 0;
;         s_xi[0] = ok; s_xi[3] = ok ? __hip_atomic_load(xcnt + s_xi[1], __ATOMIC_RELAXED, __HIP_MEMORY_SCOPE_AGENT) : 1;
;       }
;       __syncthreads();
;       xi.ok = s_xi[0]; xi.x = s_xi[1]; xi.rank = s_xi[2]; xi.nloc = s_xi[3];
;     } else grid_barrier(P.ws + L::o_bar, bgen, &s_item);
.LBB0_85:
	v_readlane_b32 s12, v254, 20
	v_readlane_b32 s13, v254, 21
	s_mov_b64 s[0:1], exec
	s_nop 0
	s_and_b64 vcc, exec, s[12:13]
	s_cbranch_vccnz .LBB0_101
	s_branch .Lxcnt_part
	s_barrier
	s_mov_b64 s[0:1], exec
	v_readlane_b32 s12, v253, 44
	v_readlane_b32 s13, v253, 45
	s_and_b64 s[12:13], s[0:1], s[12:13]
	s_mov_b64 exec, s[12:13]
	s_cbranch_execz .LBB0_96
	v_readlane_b32 s12, v252, 8
	v_readlane_b32 s13, v252, 9
	buffer_wbl2 sc1
	s_waitcnt vmcnt(0)
	s_load_dwordx2 s[12:13], s[12:13], 0x58
	s_mov_b64 s[14:15], exec
	v_mbcnt_lo_u32_b32 v1, s14, 0
	v_mbcnt_hi_u32_b32 v1, s15, v1
	v_cmp_eq_u32_e32 vcc, 0, v1
	s_waitcnt lgkmcnt(0)
	global_load_dword v0, v153, s[12:13] offset:40
	s_and_saveexec_b64 s[16:17], vcc
	s_cbranch_execz .LBB0_89
	s_bcnt1_i32_b64 s2, s[14:15]
	v_mov_b32_e32 v2, s2
	global_atomic_add v2, v153, v2, s[12:13] offset:32 sc0

; template <int G>
; __global__ void __launch_bounds__(256, 2) fwd_kernel(Params P) {
;     ...
;       if (tid == 0) {
;         int* xcnt = (int*)(P.ws + L::o_bar + 512);
;         int ok = (__hip_atomic_load(xcnt + 8, __ATOMIC_RELAXED, __HIP_MEMORY_SCOPE_AGENT) == 0) ? 1 : 0;
;         for (int q = 0; q < 8; ++q) if (__hip_atomic_load(xcnt + q, __ATOMIC_RELAXED, __HIP_MEMORY_SCOPE_AGENT) <= 0) ok = 0;
;         s_xi[0] = ok; s_xi[3] = ok ? __hip_atomic_load(xcnt + s_xi[1], __ATOMIC_RELAXED, __HIP_MEMORY_SCOPE_AGENT) : 1;
;       }
;       __syncthreads();
;       xi.ok = s_xi[0]; xi.x = s_xi[1]; xi.rank = s_xi[2]; xi.nloc = s_xi[3];
.Lxcnt_part:
	s_barrier
	s_and_saveexec_b64 s[12:13], s[54:55]
	s_cbranch_execz .LBB0_100
	v_readlane_b32 s20, v253, 38
	v_readlane_b32 s22, v253, 40
	v_readlane_b32 s23, v253, 41
	s_nop 4
	global_load_dword v0, v153, s[22:23] offset:1568 sc1
	global_load_dword v1, v153, s[22:23] offset:1536 sc1
	global_load_dword v2, v153, s[22:23] offset:1540 sc1
	global_load_dword v3, v153, s[22:23] offset:1544 sc1
	global_load_dword v4, v153, s[22:23] offset:1548 sc1
	global_load_dword v5, v153, s[22:23] offset:1552 sc1
	global_load_dword v6, v153, s[22:23] offset:1556 sc1
	global_load_dword v7, v153, s[22:23] offset:1560 sc1
	global_load_dword v8, v153, s[22:23] offset:1564 sc1
	v_readlane_b32 s21, v253, 39
	s_waitcnt vmcnt(8)
	v_cmp_eq_u32_e32 vcc, 0, v0
	s_waitcnt vmcnt(0)
	v_min3_i32 v0, v8, v7, v6
	v_min3_i32 v0, v0, v5, v4
	v_min3_i32 v0, v0, v3, v2
	v_min_i32_e32 v0, v0, v1
	v_cmp_lt_i32_e64 s[0:1], 0, v0
	s_and_b64 s[0:1], s[0:1], vcc
	v_mov_b32_e32 v1, 0x12000
	v_cndmask_b32_e64 v0, 0, 1, s[0:1]
	ds_write_b32 v1, v0
	s_andn2_b64 vcc, exec, s[0:1]
	v_mov_b32_e32 v0, 1
	s_cbranch_vccnz .LBB0_99
	v_mov_b32_e32 v0, 0x12004
	ds_read_b32 v0, v0
	v_readlane_b32 s20, v253, 38
	v_readlane_b32 s22, v253, 40
	v_readlane_b32 s23, v253, 41
	v_readlane_b32 s21, v253, 39
	s_waitcnt lgkmcnt(0)
	v_ashrrev_i32_e32 v1, 31, v0
	v_lshlrev_b64 v[0:1], 2, v[0:1]
	v_lshl_add_u64 v[0:1], s[22:23], 0, v[0:1]
	global_load_dword v0, v[0:1], off offset:1536 sc1

; template <int G>
; __global__ void __launch_bounds__(256, 2) fwd_kernel(Params P) {
;     ...
;       __syncthreads();
;       xi.ok = s_xi[0]; xi.x = s_xi[1]; xi.rank = s_xi[2]; xi.nloc = s_xi[3];
;     } else grid_barrier(P.ws + L::o_bar, bgen, &s_item);
.LBB0_100:
	s_or_b64 exec, exec, s[12:13]
	v_mov_b32_e32 v0, 0x12000
	s_waitcnt lgkmcnt(0)
	s_barrier
	ds_read_b128 v[0:3], v0
	s_add_i32 s16, s6, 1
	s_waitcnt lgkmcnt(0)
	v_readfirstlane_b32 s0, v3
	s_nop 1
	v_writelane_b32 v253, s0, 46
	v_readfirstlane_b32 s0, v2
	v_readfirstlane_b32 s1, v1
	s_nop 0
	v_writelane_b32 v253, s0, 47
	v_readfirstlane_b32 s0, v0
	s_nop 1
	v_writelane_b32 v253, s0, 60
	s_nop 1
	v_writelane_b32 v253, s1, 61
